# speedup vs baseline: 1.0474x; 1.0115x over previous
.Lfz1_c0:
	s_and_b32 s27, s86, 0xc000
	v_add_u32_e32 v241, s27, v233
	ds_read_b128 v[144:147], v241 offset:0
	v_xor_b32_e32 v240, 32, v241
	ds_read_b128 v[148:151], v240 offset:0
	v_xor_b32_e32 v239, 64, v241
	ds_read_b128 v[152:155], v239 offset:0
	v_xor_b32_e32 v0, 0x60, v241
	ds_read_b128 v[156:159], v0 offset:0
	s_waitcnt lgkmcnt(0)
	v_mfma_f32_32x32x16_bf16 v[212:227], v[144:147], v[176:179], 0
	v_mfma_f32_32x32x16_bf16 v[212:227], v[148:151], v[180:183], v[212:227]
	v_mfma_f32_32x32x16_bf16 v[212:227], v[152:155], v[184:187], v[212:227]
	v_mfma_f32_32x32x16_bf16 v[212:227], v[156:159], v[188:191], v[212:227]
	ds_read_b128 v[144:147], v241 offset:0x80
	ds_read_b128 v[148:151], v240 offset:0x80
	ds_read_b128 v[152:155], v239 offset:0x80
	ds_read_b128 v[156:159], v0 offset:0x80
	v_cmp_eq_f32_e32 vcc, 0, v238
	v_cmp_eq_f32_e64 s[10:11], 0, v237
	s_and_b64 s[0:1], vcc, s[10:11]
	s_cmp_eq_u64 s[0:1], exec
	s_waitcnt lgkmcnt(0)
	v_mfma_f32_32x32x16_bf16 v[160:175], v[144:147], v[192:195], 0
	v_mfma_f32_32x32x16_bf16 v[160:175], v[148:151], v[196:199], v[160:175]
	v_mfma_f32_32x32x16_bf16 v[160:175], v[152:155], v[200:203], v[160:175]
	v_mfma_f32_32x32x16_bf16 v[160:175], v[156:159], v[204:207], v[160:175]
	s_cbranch_scc0 .LBB0_397
	v_exp_f32_e32 v144, v212
	v_exp_f32_e32 v145, v213
	v_exp_f32_e32 v146, v214
	v_exp_f32_e32 v147, v215
	v_exp_f32_e32 v148, v216
	v_exp_f32_e32 v149, v217
	v_exp_f32_e32 v150, v218
	v_exp_f32_e32 v151, v219
	v_exp_f32_e32 v152, v220
	v_exp_f32_e32 v153, v221
	v_exp_f32_e32 v154, v222
	v_exp_f32_e32 v155, v223
	v_exp_f32_e32 v156, v224
	v_exp_f32_e32 v157, v225
	v_exp_f32_e32 v158, v226
	v_exp_f32_e32 v159, v227
	v_add_f32_e32 v252, v144, v145
	v_add_f32_e32 v253, v146, v147
	v_add_f32_e32 v254, v148, v149
	v_add_f32_e32 v255, v150, v151
	v_add_f32_e32 v252, v252, v152
	v_add_f32_e32 v253, v253, v153
	v_add_f32_e32 v254, v254, v154
	v_add_f32_e32 v255, v255, v155
	v_add_f32_e32 v252, v252, v156
	v_add_f32_e32 v253, v253, v157
	v_add_f32_e32 v254, v254, v158
	v_add_f32_e32 v255, v255, v159
	v_cvt_pk_bf16_f32 v216, v144, v145
	v_cvt_pk_bf16_f32 v217, v146, v147
	v_add_f32_e32 v252, v252, v253
	v_add_f32_e32 v254, v254, v255
	v_cvt_pk_bf16_f32 v218, v148, v149
	v_cvt_pk_bf16_f32 v219, v150, v151
	v_cvt_pk_bf16_f32 v224, v152, v153
	v_add_f32_e32 v252, v252, v254
	v_cvt_pk_bf16_f32 v225, v154, v155
	v_cvt_pk_bf16_f32 v226, v156, v157
	v_cvt_pk_bf16_f32 v227, v158, v159
	v_cmp_lt_f32_e32 vcc, s58, v252
	v_cmp_gt_f32_e64 s[10:11], s59, v252
	s_and_b64 s[0:1], vcc, s[10:11]
	s_cmp_lg_u64 s[0:1], exec
	s_cbranch_scc1 .LBB0_432
	v_add_f32_e32 v15, v15, v252
	v_exp_f32_e32 v144, v160
	v_exp_f32_e32 v145, v161
	v_exp_f32_e32 v146, v162
	v_exp_f32_e32 v147, v163
	v_exp_f32_e32 v148, v164
	v_exp_f32_e32 v149, v165
	v_exp_f32_e32 v150, v166
	v_exp_f32_e32 v151, v167
	v_exp_f32_e32 v152, v168
	v_exp_f32_e32 v153, v169
	v_exp_f32_e32 v154, v170
	v_exp_f32_e32 v155, v171
	v_exp_f32_e32 v156, v172
	v_exp_f32_e32 v157, v173
	v_exp_f32_e32 v158, v174
	v_exp_f32_e32 v159, v175
	v_add_f32_e32 v252, v144, v145
	v_add_f32_e32 v253, v146, v147
	v_add_f32_e32 v254, v148, v149
	v_add_f32_e32 v255, v150, v151
	v_add_f32_e32 v252, v252, v152
	v_add_f32_e32 v253, v253, v153
	v_add_f32_e32 v254, v254, v154
	v_add_f32_e32 v255, v255, v155
	v_add_f32_e32 v252, v252, v156
	v_add_f32_e32 v253, v253, v157
	v_add_f32_e32 v254, v254, v158
	v_add_f32_e32 v255, v255, v159
	v_cvt_pk_bf16_f32 v212, v144, v145
	v_cvt_pk_bf16_f32 v213, v146, v147
	v_add_f32_e32 v252, v252, v253
	v_add_f32_e32 v254, v254, v255
	v_cvt_pk_bf16_f32 v214, v148, v149
	v_cvt_pk_bf16_f32 v215, v150, v151
	v_cvt_pk_bf16_f32 v220, v152, v153
	v_add_f32_e32 v252, v252, v254
	v_cvt_pk_bf16_f32 v221, v154, v155
	v_cvt_pk_bf16_f32 v222, v156, v157
	v_cvt_pk_bf16_f32 v223, v158, v159
	v_cmp_lt_f32_e32 vcc, s58, v252
	v_cmp_gt_f32_e64 s[10:11], s59, v252
	s_and_b64 s[0:1], vcc, s[10:11]
	s_cmp_lg_u64 s[0:1], exec
	s_cbranch_scc1 .Lfzsb1_c0
	v_add_f32_e32 v14, v14, v252
	s_branch .LBB0_413

.LBB0_413:
	v_add_u32_e32 v242, s27, v234
	ds_read_b64_tr_b16 v[160:161], v242 offset:0x0
	ds_read_b64_tr_b16 v[162:163], v242 offset:0x100
	ds_read_b64_tr_b16 v[164:165], v242 offset:0x1000
	ds_read_b64_tr_b16 v[166:167], v242 offset:0x1100
	s_waitcnt lgkmcnt(2)
	s_nop 0
	v_mfma_f32_32x32x16_bf16 v[128:143], v[216:219], v[160:163], v[128:143]
	ds_read_b64_tr_b16 v[168:169], v242 offset:0x200
	v_mfma_f32_32x32x16_bf16 v[96:111], v[212:215], v[160:163], v[96:111]
	ds_read_b64_tr_b16 v[170:171], v242 offset:0x300
	s_waitcnt lgkmcnt(2)
	v_mfma_f32_32x32x16_bf16 v[128:143], v[224:227], v[164:167], v[128:143]
	ds_read_b64_tr_b16 v[172:173], v242 offset:0x1200
	v_mfma_f32_32x32x16_bf16 v[96:111], v[220:223], v[164:167], v[96:111]
	ds_read_b64_tr_b16 v[174:175], v242 offset:0x1300
	s_waitcnt lgkmcnt(2)
	v_mfma_f32_32x32x16_bf16 v[112:127], v[216:219], v[168:171], v[112:127]
	ds_read_b64_tr_b16 v[160:161], v242 offset:0x400
	v_mfma_f32_32x32x16_bf16 v[80:95], v[212:215], v[168:171], v[80:95]
	ds_read_b64_tr_b16 v[162:163], v242 offset:0x500
	s_waitcnt lgkmcnt(2)
	v_mfma_f32_32x32x16_bf16 v[112:127], v[224:227], v[172:175], v[112:127]
	ds_read_b64_tr_b16 v[164:165], v242 offset:0x1400
	v_mfma_f32_32x32x16_bf16 v[80:95], v[220:223], v[172:175], v[80:95]
	ds_read_b64_tr_b16 v[166:167], v242 offset:0x1500
	ds_read_b128 v[144:147], v241 offset:0x2000
	ds_read_b128 v[148:151], v240 offset:0x2000
	ds_read_b128 v[152:155], v239 offset:0x2000
	ds_read_b128 v[156:159], v0 offset:0x2000
	s_waitcnt lgkmcnt(6)
	v_mfma_f32_32x32x16_bf16 v[64:79], v[216:219], v[160:163], v[64:79]
	ds_read_b64_tr_b16 v[168:169], v242 offset:0x600
	v_mfma_f32_32x32x16_bf16 v[32:47], v[212:215], v[160:163], v[32:47]
	ds_read_b64_tr_b16 v[170:171], v242 offset:0x700
	s_waitcnt lgkmcnt(6)
	v_mfma_f32_32x32x16_bf16 v[64:79], v[224:227], v[164:167], v[64:79]
	ds_read_b64_tr_b16 v[172:173], v242 offset:0x1600
	v_mfma_f32_32x32x16_bf16 v[32:47], v[220:223], v[164:167], v[32:47]
	ds_read_b64_tr_b16 v[174:175], v242 offset:0x1700
	s_waitcnt lgkmcnt(2)
	v_mfma_f32_32x32x16_bf16 v[48:63], v[216:219], v[168:171], v[48:63]
	v_mfma_f32_32x32x16_bf16 v[16:31], v[212:215], v[168:171], v[16:31]
	s_waitcnt lgkmcnt(0)
	v_mfma_f32_32x32x16_bf16 v[48:63], v[224:227], v[172:175], v[48:63]
	v_mfma_f32_32x32x16_bf16 v[16:31], v[220:223], v[172:175], v[16:31]
	s_waitcnt lgkmcnt(0)
	v_mfma_f32_32x32x16_bf16 v[212:227], v[144:147], v[176:179], 0
	v_mfma_f32_32x32x16_bf16 v[212:227], v[148:151], v[180:183], v[212:227]
	v_mfma_f32_32x32x16_bf16 v[212:227], v[152:155], v[184:187], v[212:227]
	v_mfma_f32_32x32x16_bf16 v[212:227], v[156:159], v[188:191], v[212:227]
	ds_read_b128 v[144:147], v241 offset:0x2080
	ds_read_b128 v[148:151], v240 offset:0x2080
	ds_read_b128 v[152:155], v239 offset:0x2080
	ds_read_b128 v[156:159], v0 offset:0x2080
	v_cmp_eq_f32_e32 vcc, 0, v238
	v_cmp_eq_f32_e64 s[10:11], 0, v237
	s_and_b64 s[0:1], vcc, s[10:11]
	s_cmp_eq_u64 s[0:1], exec
	s_waitcnt lgkmcnt(0)
	v_mfma_f32_32x32x16_bf16 v[160:175], v[144:147], v[192:195], 0
	v_mfma_f32_32x32x16_bf16 v[160:175], v[148:151], v[196:199], v[160:175]
	v_mfma_f32_32x32x16_bf16 v[160:175], v[152:155], v[200:203], v[160:175]
	v_mfma_f32_32x32x16_bf16 v[160:175], v[156:159], v[204:207], v[160:175]
	s_cbranch_scc0 .Lfz2o_c0
	v_exp_f32_e32 v144, v212
	v_exp_f32_e32 v145, v213
	v_exp_f32_e32 v146, v214
	v_exp_f32_e32 v147, v215
	v_exp_f32_e32 v148, v216
	v_exp_f32_e32 v149, v217
	v_exp_f32_e32 v150, v218
	v_exp_f32_e32 v151, v219
	v_exp_f32_e32 v152, v220
	v_exp_f32_e32 v153, v221
	v_exp_f32_e32 v154, v222
	v_exp_f32_e32 v155, v223
	v_exp_f32_e32 v156, v224
	v_exp_f32_e32 v157, v225
	v_exp_f32_e32 v158, v226
	v_exp_f32_e32 v159, v227
	v_add_f32_e32 v252, v144, v145
	v_add_f32_e32 v253, v146, v147
	v_add_f32_e32 v254, v148, v149
	v_add_f32_e32 v255, v150, v151
	v_add_f32_e32 v252, v252, v152
	v_add_f32_e32 v253, v253, v153
	v_add_f32_e32 v254, v254, v154
	v_add_f32_e32 v255, v255, v155
	v_add_f32_e32 v252, v252, v156
	v_add_f32_e32 v253, v253, v157
	v_add_f32_e32 v254, v254, v158
	v_add_f32_e32 v255, v255, v159
	v_cvt_pk_bf16_f32 v6, v144, v145
	v_cvt_pk_bf16_f32 v7, v146, v147
	v_add_f32_e32 v252, v252, v253
	v_add_f32_e32 v254, v254, v255
	v_cvt_pk_bf16_f32 v8, v148, v149
	v_cvt_pk_bf16_f32 v9, v150, v151
	v_cvt_pk_bf16_f32 v208, v152, v153
	v_add_f32_e32 v252, v252, v254
	v_cvt_pk_bf16_f32 v209, v154, v155
	v_cvt_pk_bf16_f32 v210, v156, v157
	v_cvt_pk_bf16_f32 v211, v158, v159
	v_cmp_lt_f32_e32 vcc, s58, v252
	v_cmp_gt_f32_e64 s[10:11], s59, v252
	s_and_b64 s[0:1], vcc, s[10:11]
	s_cmp_lg_u64 s[0:1], exec
	s_cbranch_scc1 .LBB0_444
	v_add_f32_e32 v15, v15, v252
	v_exp_f32_e32 v144, v160
	v_exp_f32_e32 v145, v161
	v_exp_f32_e32 v146, v162
	v_exp_f32_e32 v147, v163
	v_exp_f32_e32 v148, v164
	v_exp_f32_e32 v149, v165
	v_exp_f32_e32 v150, v166
	v_exp_f32_e32 v151, v167
	v_exp_f32_e32 v152, v168
	v_exp_f32_e32 v153, v169
	v_exp_f32_e32 v154, v170
	v_exp_f32_e32 v155, v171
	v_exp_f32_e32 v156, v172
	v_exp_f32_e32 v157, v173
	v_exp_f32_e32 v158, v174
	v_exp_f32_e32 v159, v175
	v_add_f32_e32 v252, v144, v145
	v_add_f32_e32 v253, v146, v147
	v_add_f32_e32 v254, v148, v149
	v_add_f32_e32 v255, v150, v151
	v_add_f32_e32 v252, v252, v152
	v_add_f32_e32 v253, v253, v153
	v_add_f32_e32 v254, v254, v154
	v_add_f32_e32 v255, v255, v155
	v_add_f32_e32 v252, v252, v156
	v_add_f32_e32 v253, v253, v157
	v_add_f32_e32 v254, v254, v158
	v_add_f32_e32 v255, v255, v159
	v_cvt_pk_bf16_f32 v2, v144, v145
	v_cvt_pk_bf16_f32 v3, v146, v147
	v_add_f32_e32 v252, v252, v253
	v_add_f32_e32 v254, v254, v255
	v_cvt_pk_bf16_f32 v4, v148, v149
	v_cvt_pk_bf16_f32 v5, v150, v151
	v_cvt_pk_bf16_f32 v10, v152, v153
	v_add_f32_e32 v252, v252, v254
	v_cvt_pk_bf16_f32 v11, v154, v155
	v_cvt_pk_bf16_f32 v12, v156, v157
	v_cvt_pk_bf16_f32 v13, v158, v159
	v_cmp_lt_f32_e32 vcc, s58, v252
	v_cmp_gt_f32_e64 s[10:11], s59, v252
	s_and_b64 s[0:1], vcc, s[10:11]
	s_cmp_lg_u64 s[0:1], exec
	s_cbranch_scc1 .Lfzsb2_c0
	v_add_f32_e32 v14, v14, v252
	s_branch .LBB0_429

.Lfz1_c1:
	s_and_b32 s27, s77, 0xc000
	v_add_u32_e32 v241, s27, v233
	ds_read_b128 v[144:147], v241 offset:0
	v_xor_b32_e32 v240, 32, v241
	ds_read_b128 v[148:151], v240 offset:0
	v_xor_b32_e32 v239, 64, v241
	ds_read_b128 v[152:155], v239 offset:0
	v_xor_b32_e32 v0, 0x60, v241
	ds_read_b128 v[156:159], v0 offset:0
	s_waitcnt lgkmcnt(0)
	v_mfma_f32_32x32x16_bf16 v[212:227], v[144:147], v[176:179], 0
	v_mfma_f32_32x32x16_bf16 v[212:227], v[148:151], v[180:183], v[212:227]
	v_mfma_f32_32x32x16_bf16 v[212:227], v[152:155], v[184:187], v[212:227]
	v_mfma_f32_32x32x16_bf16 v[212:227], v[156:159], v[188:191], v[212:227]
	ds_read_b128 v[144:147], v241 offset:0x80
	ds_read_b128 v[148:151], v240 offset:0x80
	ds_read_b128 v[152:155], v239 offset:0x80
	ds_read_b128 v[156:159], v0 offset:0x80
	v_cmp_eq_f32_e32 vcc, 0, v238
	v_cmp_eq_f32_e64 s[10:11], 0, v237
	s_and_b64 s[0:1], vcc, s[10:11]
	s_cmp_eq_u64 s[0:1], exec
	s_waitcnt lgkmcnt(0)
	v_mfma_f32_32x32x16_bf16 v[160:175], v[144:147], v[192:195], 0
	v_mfma_f32_32x32x16_bf16 v[160:175], v[148:151], v[196:199], v[160:175]
	v_mfma_f32_32x32x16_bf16 v[160:175], v[152:155], v[200:203], v[160:175]
	v_mfma_f32_32x32x16_bf16 v[160:175], v[156:159], v[204:207], v[160:175]
	s_cbranch_scc0 .LBB0_1251
	v_exp_f32_e32 v144, v212
	v_exp_f32_e32 v145, v213
	v_exp_f32_e32 v146, v214
	v_exp_f32_e32 v147, v215
	v_exp_f32_e32 v148, v216
	v_exp_f32_e32 v149, v217
	v_exp_f32_e32 v150, v218
	v_exp_f32_e32 v151, v219
	v_exp_f32_e32 v152, v220
	v_exp_f32_e32 v153, v221
	v_exp_f32_e32 v154, v222
	v_exp_f32_e32 v155, v223
	v_exp_f32_e32 v156, v224
	v_exp_f32_e32 v157, v225
	v_exp_f32_e32 v158, v226
	v_exp_f32_e32 v159, v227
	v_add_f32_e32 v252, v144, v145
	v_add_f32_e32 v253, v146, v147
	v_add_f32_e32 v254, v148, v149
	v_add_f32_e32 v255, v150, v151
	v_add_f32_e32 v252, v252, v152
	v_add_f32_e32 v253, v253, v153
	v_add_f32_e32 v254, v254, v154
	v_add_f32_e32 v255, v255, v155
	v_add_f32_e32 v252, v252, v156
	v_add_f32_e32 v253, v253, v157
	v_add_f32_e32 v254, v254, v158
	v_add_f32_e32 v255, v255, v159
	v_cvt_pk_bf16_f32 v216, v144, v145
	v_cvt_pk_bf16_f32 v217, v146, v147
	v_add_f32_e32 v252, v252, v253
	v_add_f32_e32 v254, v254, v255
	v_cvt_pk_bf16_f32 v218, v148, v149
	v_cvt_pk_bf16_f32 v219, v150, v151
	v_cvt_pk_bf16_f32 v224, v152, v153
	v_add_f32_e32 v252, v252, v254
	v_cvt_pk_bf16_f32 v225, v154, v155
	v_cvt_pk_bf16_f32 v226, v156, v157
	v_cvt_pk_bf16_f32 v227, v158, v159
	v_cmp_lt_f32_e32 vcc, s52, v252
	v_cmp_gt_f32_e64 s[10:11], s53, v252
	s_and_b64 s[0:1], vcc, s[10:11]
	s_cmp_lg_u64 s[0:1], exec
	s_cbranch_scc1 .LBB0_1286
	v_add_f32_e32 v15, v15, v252
	v_exp_f32_e32 v144, v160
	v_exp_f32_e32 v145, v161
	v_exp_f32_e32 v146, v162
	v_exp_f32_e32 v147, v163
	v_exp_f32_e32 v148, v164
	v_exp_f32_e32 v149, v165
	v_exp_f32_e32 v150, v166
	v_exp_f32_e32 v151, v167
	v_exp_f32_e32 v152, v168
	v_exp_f32_e32 v153, v169
	v_exp_f32_e32 v154, v170
	v_exp_f32_e32 v155, v171
	v_exp_f32_e32 v156, v172
	v_exp_f32_e32 v157, v173
	v_exp_f32_e32 v158, v174
	v_exp_f32_e32 v159, v175
	v_add_f32_e32 v252, v144, v145
	v_add_f32_e32 v253, v146, v147
	v_add_f32_e32 v254, v148, v149
	v_add_f32_e32 v255, v150, v151
	v_add_f32_e32 v252, v252, v152
	v_add_f32_e32 v253, v253, v153
	v_add_f32_e32 v254, v254, v154
	v_add_f32_e32 v255, v255, v155
	v_add_f32_e32 v252, v252, v156
	v_add_f32_e32 v253, v253, v157
	v_add_f32_e32 v254, v254, v158
	v_add_f32_e32 v255, v255, v159
	v_cvt_pk_bf16_f32 v212, v144, v145
	v_cvt_pk_bf16_f32 v213, v146, v147
	v_add_f32_e32 v252, v252, v253
	v_add_f32_e32 v254, v254, v255
	v_cvt_pk_bf16_f32 v214, v148, v149
	v_cvt_pk_bf16_f32 v215, v150, v151
	v_cvt_pk_bf16_f32 v220, v152, v153
	v_add_f32_e32 v252, v252, v254
	v_cvt_pk_bf16_f32 v221, v154, v155
	v_cvt_pk_bf16_f32 v222, v156, v157
	v_cvt_pk_bf16_f32 v223, v158, v159
	v_cmp_lt_f32_e32 vcc, s52, v252
	v_cmp_gt_f32_e64 s[10:11], s53, v252
	s_and_b64 s[0:1], vcc, s[10:11]
	s_cmp_lg_u64 s[0:1], exec
	s_cbranch_scc1 .Lfzsb1_c1
	v_add_f32_e32 v14, v14, v252
	s_branch .LBB0_1267

.LBB0_1267:
	v_add_u32_e32 v242, s27, v234
	ds_read_b64_tr_b16 v[160:161], v242 offset:0x0
	ds_read_b64_tr_b16 v[162:163], v242 offset:0x100
	ds_read_b64_tr_b16 v[164:165], v242 offset:0x1000
	ds_read_b64_tr_b16 v[166:167], v242 offset:0x1100
	s_waitcnt lgkmcnt(2)
	s_nop 0
	v_mfma_f32_32x32x16_bf16 v[128:143], v[216:219], v[160:163], v[128:143]
	ds_read_b64_tr_b16 v[168:169], v242 offset:0x200
	v_mfma_f32_32x32x16_bf16 v[96:111], v[212:215], v[160:163], v[96:111]
	ds_read_b64_tr_b16 v[170:171], v242 offset:0x300
	s_waitcnt lgkmcnt(2)
	v_mfma_f32_32x32x16_bf16 v[128:143], v[224:227], v[164:167], v[128:143]
	ds_read_b64_tr_b16 v[172:173], v242 offset:0x1200
	v_mfma_f32_32x32x16_bf16 v[96:111], v[220:223], v[164:167], v[96:111]
	ds_read_b64_tr_b16 v[174:175], v242 offset:0x1300
	s_waitcnt lgkmcnt(2)
	v_mfma_f32_32x32x16_bf16 v[112:127], v[216:219], v[168:171], v[112:127]
	ds_read_b64_tr_b16 v[160:161], v242 offset:0x400
	v_mfma_f32_32x32x16_bf16 v[80:95], v[212:215], v[168:171], v[80:95]
	ds_read_b64_tr_b16 v[162:163], v242 offset:0x500
	s_waitcnt lgkmcnt(2)
	v_mfma_f32_32x32x16_bf16 v[112:127], v[224:227], v[172:175], v[112:127]
	ds_read_b64_tr_b16 v[164:165], v242 offset:0x1400
	v_mfma_f32_32x32x16_bf16 v[80:95], v[220:223], v[172:175], v[80:95]
	ds_read_b64_tr_b16 v[166:167], v242 offset:0x1500
	ds_read_b128 v[144:147], v241 offset:0x2000
	ds_read_b128 v[148:151], v240 offset:0x2000
	ds_read_b128 v[152:155], v239 offset:0x2000
	ds_read_b128 v[156:159], v0 offset:0x2000
	s_waitcnt lgkmcnt(6)
	v_mfma_f32_32x32x16_bf16 v[64:79], v[216:219], v[160:163], v[64:79]
	ds_read_b64_tr_b16 v[168:169], v242 offset:0x600
	v_mfma_f32_32x32x16_bf16 v[48:63], v[212:215], v[160:163], v[48:63]
	ds_read_b64_tr_b16 v[170:171], v242 offset:0x700
	s_waitcnt lgkmcnt(6)
	v_mfma_f32_32x32x16_bf16 v[64:79], v[224:227], v[164:167], v[64:79]
	ds_read_b64_tr_b16 v[172:173], v242 offset:0x1600
	v_mfma_f32_32x32x16_bf16 v[48:63], v[220:223], v[164:167], v[48:63]
	ds_read_b64_tr_b16 v[174:175], v242 offset:0x1700
	s_waitcnt lgkmcnt(2)
	v_mfma_f32_32x32x16_bf16 v[32:47], v[216:219], v[168:171], v[32:47]
	v_mfma_f32_32x32x16_bf16 v[16:31], v[212:215], v[168:171], v[16:31]
	s_waitcnt lgkmcnt(0)
	v_mfma_f32_32x32x16_bf16 v[32:47], v[224:227], v[172:175], v[32:47]
	v_mfma_f32_32x32x16_bf16 v[16:31], v[220:223], v[172:175], v[16:31]
	s_waitcnt lgkmcnt(0)
	v_mfma_f32_32x32x16_bf16 v[212:227], v[144:147], v[176:179], 0
	v_mfma_f32_32x32x16_bf16 v[212:227], v[148:151], v[180:183], v[212:227]
	v_mfma_f32_32x32x16_bf16 v[212:227], v[152:155], v[184:187], v[212:227]
	v_mfma_f32_32x32x16_bf16 v[212:227], v[156:159], v[188:191], v[212:227]
	ds_read_b128 v[144:147], v241 offset:0x2080
	ds_read_b128 v[148:151], v240 offset:0x2080
	ds_read_b128 v[152:155], v239 offset:0x2080
	ds_read_b128 v[156:159], v0 offset:0x2080
	v_cmp_eq_f32_e32 vcc, 0, v238
	v_cmp_eq_f32_e64 s[10:11], 0, v237
	s_and_b64 s[0:1], vcc, s[10:11]
	s_cmp_eq_u64 s[0:1], exec
	s_waitcnt lgkmcnt(0)
	v_mfma_f32_32x32x16_bf16 v[160:175], v[144:147], v[192:195], 0
	v_mfma_f32_32x32x16_bf16 v[160:175], v[148:151], v[196:199], v[160:175]
	v_mfma_f32_32x32x16_bf16 v[160:175], v[152:155], v[200:203], v[160:175]
	v_mfma_f32_32x32x16_bf16 v[160:175], v[156:159], v[204:207], v[160:175]
	s_cbranch_scc0 .Lfz2o_c1
	v_exp_f32_e32 v144, v212
	v_exp_f32_e32 v145, v213
	v_exp_f32_e32 v146, v214
	v_exp_f32_e32 v147, v215
	v_exp_f32_e32 v148, v216
	v_exp_f32_e32 v149, v217
	v_exp_f32_e32 v150, v218
	v_exp_f32_e32 v151, v219
	v_exp_f32_e32 v152, v220
	v_exp_f32_e32 v153, v221
	v_exp_f32_e32 v154, v222
	v_exp_f32_e32 v155, v223
	v_exp_f32_e32 v156, v224
	v_exp_f32_e32 v157, v225
	v_exp_f32_e32 v158, v226
	v_exp_f32_e32 v159, v227
	v_add_f32_e32 v252, v144, v145
	v_add_f32_e32 v253, v146, v147
	v_add_f32_e32 v254, v148, v149
	v_add_f32_e32 v255, v150, v151
	v_add_f32_e32 v252, v252, v152
	v_add_f32_e32 v253, v253, v153
	v_add_f32_e32 v254, v254, v154
	v_add_f32_e32 v255, v255, v155
	v_add_f32_e32 v252, v252, v156
	v_add_f32_e32 v253, v253, v157
	v_add_f32_e32 v254, v254, v158
	v_add_f32_e32 v255, v255, v159
	v_cvt_pk_bf16_f32 v6, v144, v145
	v_cvt_pk_bf16_f32 v7, v146, v147
	v_add_f32_e32 v252, v252, v253
	v_add_f32_e32 v254, v254, v255
	v_cvt_pk_bf16_f32 v8, v148, v149
	v_cvt_pk_bf16_f32 v9, v150, v151
	v_cvt_pk_bf16_f32 v208, v152, v153
	v_add_f32_e32 v252, v252, v254
	v_cvt_pk_bf16_f32 v209, v154, v155
	v_cvt_pk_bf16_f32 v210, v156, v157
	v_cvt_pk_bf16_f32 v211, v158, v159
	v_cmp_lt_f32_e32 vcc, s52, v252
	v_cmp_gt_f32_e64 s[10:11], s53, v252
	s_and_b64 s[0:1], vcc, s[10:11]
	s_cmp_lg_u64 s[0:1], exec
	s_cbranch_scc1 .LBB0_1298
	v_add_f32_e32 v15, v15, v252
	v_exp_f32_e32 v144, v160
	v_exp_f32_e32 v145, v161
	v_exp_f32_e32 v146, v162
	v_exp_f32_e32 v147, v163
	v_exp_f32_e32 v148, v164
	v_exp_f32_e32 v149, v165
	v_exp_f32_e32 v150, v166
	v_exp_f32_e32 v151, v167
	v_exp_f32_e32 v152, v168
	v_exp_f32_e32 v153, v169
	v_exp_f32_e32 v154, v170
	v_exp_f32_e32 v155, v171
	v_exp_f32_e32 v156, v172
	v_exp_f32_e32 v157, v173
	v_exp_f32_e32 v158, v174
	v_exp_f32_e32 v159, v175
	v_add_f32_e32 v252, v144, v145
	v_add_f32_e32 v253, v146, v147
	v_add_f32_e32 v254, v148, v149
	v_add_f32_e32 v255, v150, v151
	v_add_f32_e32 v252, v252, v152
	v_add_f32_e32 v253, v253, v153
	v_add_f32_e32 v254, v254, v154
	v_add_f32_e32 v255, v255, v155
	v_add_f32_e32 v252, v252, v156
	v_add_f32_e32 v253, v253, v157
	v_add_f32_e32 v254, v254, v158
	v_add_f32_e32 v255, v255, v159
	v_cvt_pk_bf16_f32 v2, v144, v145
	v_cvt_pk_bf16_f32 v3, v146, v147
	v_add_f32_e32 v252, v252, v253
	v_add_f32_e32 v254, v254, v255
	v_cvt_pk_bf16_f32 v4, v148, v149
	v_cvt_pk_bf16_f32 v5, v150, v151
	v_cvt_pk_bf16_f32 v10, v152, v153
	v_add_f32_e32 v252, v252, v254
	v_cvt_pk_bf16_f32 v11, v154, v155
	v_cvt_pk_bf16_f32 v12, v156, v157
	v_cvt_pk_bf16_f32 v13, v158, v159
	v_cmp_lt_f32_e32 vcc, s52, v252
	v_cmp_gt_f32_e64 s[10:11], s53, v252
	s_and_b64 s[0:1], vcc, s[10:11]
	s_cmp_lg_u64 s[0:1], exec
	s_cbranch_scc1 .Lfzsb2_c1
	v_add_f32_e32 v14, v14, v252
	s_branch .LBB0_1283

.Lfz1_c2:
	s_and_b32 s27, s68, 0xc000
	v_add_u32_e32 v241, s27, v233
	ds_read_b128 v[144:147], v241 offset:0
	v_xor_b32_e32 v240, 32, v241
	ds_read_b128 v[148:151], v240 offset:0
	v_xor_b32_e32 v239, 64, v241
	ds_read_b128 v[152:155], v239 offset:0
	v_xor_b32_e32 v0, 0x60, v241
	ds_read_b128 v[156:159], v0 offset:0
	s_waitcnt lgkmcnt(0)
	v_mfma_f32_32x32x16_bf16 v[212:227], v[144:147], v[176:179], 0
	v_mfma_f32_32x32x16_bf16 v[212:227], v[148:151], v[180:183], v[212:227]
	v_mfma_f32_32x32x16_bf16 v[212:227], v[152:155], v[184:187], v[212:227]
	v_mfma_f32_32x32x16_bf16 v[212:227], v[156:159], v[188:191], v[212:227]
	ds_read_b128 v[144:147], v241 offset:0x80
	ds_read_b128 v[148:151], v240 offset:0x80
	ds_read_b128 v[152:155], v239 offset:0x80
	ds_read_b128 v[156:159], v0 offset:0x80
	v_cmp_eq_f32_e32 vcc, 0, v238
	v_cmp_eq_f32_e64 s[6:7], 0, v237
	s_and_b64 s[0:1], vcc, s[6:7]
	s_cmp_eq_u64 s[0:1], exec
	s_waitcnt lgkmcnt(0)
	v_mfma_f32_32x32x16_bf16 v[160:175], v[144:147], v[192:195], 0
	v_mfma_f32_32x32x16_bf16 v[160:175], v[148:151], v[196:199], v[160:175]
	v_mfma_f32_32x32x16_bf16 v[160:175], v[152:155], v[200:203], v[160:175]
	v_mfma_f32_32x32x16_bf16 v[160:175], v[156:159], v[204:207], v[160:175]
	s_cbranch_scc0 .LBB0_2105
	v_exp_f32_e32 v144, v212
	v_exp_f32_e32 v145, v213
	v_exp_f32_e32 v146, v214
	v_exp_f32_e32 v147, v215
	v_exp_f32_e32 v148, v216
	v_exp_f32_e32 v149, v217
	v_exp_f32_e32 v150, v218
	v_exp_f32_e32 v151, v219
	v_exp_f32_e32 v152, v220
	v_exp_f32_e32 v153, v221
	v_exp_f32_e32 v154, v222
	v_exp_f32_e32 v155, v223
	v_exp_f32_e32 v156, v224
	v_exp_f32_e32 v157, v225
	v_exp_f32_e32 v158, v226
	v_exp_f32_e32 v159, v227
	v_add_f32_e32 v252, v144, v145
	v_add_f32_e32 v253, v146, v147
	v_add_f32_e32 v254, v148, v149
	v_add_f32_e32 v255, v150, v151
	v_add_f32_e32 v252, v252, v152
	v_add_f32_e32 v253, v253, v153
	v_add_f32_e32 v254, v254, v154
	v_add_f32_e32 v255, v255, v155
	v_add_f32_e32 v252, v252, v156
	v_add_f32_e32 v253, v253, v157
	v_add_f32_e32 v254, v254, v158
	v_add_f32_e32 v255, v255, v159
	v_cvt_pk_bf16_f32 v216, v144, v145
	v_cvt_pk_bf16_f32 v217, v146, v147
	v_add_f32_e32 v252, v252, v253
	v_add_f32_e32 v254, v254, v255
	v_cvt_pk_bf16_f32 v218, v148, v149
	v_cvt_pk_bf16_f32 v219, v150, v151
	v_cvt_pk_bf16_f32 v224, v152, v153
	v_add_f32_e32 v252, v252, v254
	v_cvt_pk_bf16_f32 v225, v154, v155
	v_cvt_pk_bf16_f32 v226, v156, v157
	v_cvt_pk_bf16_f32 v227, v158, v159
	v_cmp_lt_f32_e32 vcc, s48, v252
	v_cmp_gt_f32_e64 s[6:7], s49, v252
	s_and_b64 s[0:1], vcc, s[6:7]
	s_cmp_lg_u64 s[0:1], exec
	s_cbranch_scc1 .LBB0_2140
	v_add_f32_e32 v15, v15, v252
	v_exp_f32_e32 v144, v160
	v_exp_f32_e32 v145, v161
	v_exp_f32_e32 v146, v162
	v_exp_f32_e32 v147, v163
	v_exp_f32_e32 v148, v164
	v_exp_f32_e32 v149, v165
	v_exp_f32_e32 v150, v166
	v_exp_f32_e32 v151, v167
	v_exp_f32_e32 v152, v168
	v_exp_f32_e32 v153, v169
	v_exp_f32_e32 v154, v170
	v_exp_f32_e32 v155, v171
	v_exp_f32_e32 v156, v172
	v_exp_f32_e32 v157, v173
	v_exp_f32_e32 v158, v174
	v_exp_f32_e32 v159, v175
	v_add_f32_e32 v252, v144, v145
	v_add_f32_e32 v253, v146, v147
	v_add_f32_e32 v254, v148, v149
	v_add_f32_e32 v255, v150, v151
	v_add_f32_e32 v252, v252, v152
	v_add_f32_e32 v253, v253, v153
	v_add_f32_e32 v254, v254, v154
	v_add_f32_e32 v255, v255, v155
	v_add_f32_e32 v252, v252, v156
	v_add_f32_e32 v253, v253, v157
	v_add_f32_e32 v254, v254, v158
	v_add_f32_e32 v255, v255, v159
	v_cvt_pk_bf16_f32 v212, v144, v145
	v_cvt_pk_bf16_f32 v213, v146, v147
	v_add_f32_e32 v252, v252, v253
	v_add_f32_e32 v254, v254, v255
	v_cvt_pk_bf16_f32 v214, v148, v149
	v_cvt_pk_bf16_f32 v215, v150, v151
	v_cvt_pk_bf16_f32 v220, v152, v153
	v_add_f32_e32 v252, v252, v254
	v_cvt_pk_bf16_f32 v221, v154, v155
	v_cvt_pk_bf16_f32 v222, v156, v157
	v_cvt_pk_bf16_f32 v223, v158, v159
	v_cmp_lt_f32_e32 vcc, s48, v252
	v_cmp_gt_f32_e64 s[6:7], s49, v252
	s_and_b64 s[0:1], vcc, s[6:7]
	s_cmp_lg_u64 s[0:1], exec
	s_cbranch_scc1 .Lfzsb1_c2
	v_add_f32_e32 v14, v14, v252
	s_branch .LBB0_2121

.LBB0_2121:
	v_add_u32_e32 v242, s27, v234
	ds_read_b64_tr_b16 v[160:161], v242 offset:0x0
	ds_read_b64_tr_b16 v[162:163], v242 offset:0x100
	ds_read_b64_tr_b16 v[164:165], v242 offset:0x1000
	ds_read_b64_tr_b16 v[166:167], v242 offset:0x1100
	s_waitcnt lgkmcnt(2)
	s_nop 0
	v_mfma_f32_32x32x16_bf16 v[128:143], v[216:219], v[160:163], v[128:143]
	ds_read_b64_tr_b16 v[168:169], v242 offset:0x200
	v_mfma_f32_32x32x16_bf16 v[96:111], v[212:215], v[160:163], v[96:111]
	ds_read_b64_tr_b16 v[170:171], v242 offset:0x300
	s_waitcnt lgkmcnt(2)
	v_mfma_f32_32x32x16_bf16 v[128:143], v[224:227], v[164:167], v[128:143]
	ds_read_b64_tr_b16 v[172:173], v242 offset:0x1200
	v_mfma_f32_32x32x16_bf16 v[96:111], v[220:223], v[164:167], v[96:111]
	ds_read_b64_tr_b16 v[174:175], v242 offset:0x1300
	s_waitcnt lgkmcnt(2)
	v_mfma_f32_32x32x16_bf16 v[112:127], v[216:219], v[168:171], v[112:127]
	ds_read_b64_tr_b16 v[160:161], v242 offset:0x400
	v_mfma_f32_32x32x16_bf16 v[80:95], v[212:215], v[168:171], v[80:95]
	ds_read_b64_tr_b16 v[162:163], v242 offset:0x500
	s_waitcnt lgkmcnt(2)
	v_mfma_f32_32x32x16_bf16 v[112:127], v[224:227], v[172:175], v[112:127]
	ds_read_b64_tr_b16 v[164:165], v242 offset:0x1400
	v_mfma_f32_32x32x16_bf16 v[80:95], v[220:223], v[172:175], v[80:95]
	ds_read_b64_tr_b16 v[166:167], v242 offset:0x1500
	ds_read_b128 v[144:147], v241 offset:0x2000
	ds_read_b128 v[148:151], v240 offset:0x2000
	ds_read_b128 v[156:159], v239 offset:0x2000
	ds_read_b128 v[244:247], v0 offset:0x2000
	s_waitcnt lgkmcnt(6)
	v_mfma_f32_32x32x16_bf16 v[64:79], v[216:219], v[160:163], v[64:79]
	ds_read_b64_tr_b16 v[168:169], v242 offset:0x600
	v_mfma_f32_32x32x16_bf16 v[32:47], v[212:215], v[160:163], v[32:47]
	ds_read_b64_tr_b16 v[170:171], v242 offset:0x700
	s_waitcnt lgkmcnt(6)
	v_mfma_f32_32x32x16_bf16 v[64:79], v[224:227], v[164:167], v[64:79]
	ds_read_b64_tr_b16 v[172:173], v242 offset:0x1600
	v_mfma_f32_32x32x16_bf16 v[32:47], v[220:223], v[164:167], v[32:47]
	ds_read_b64_tr_b16 v[174:175], v242 offset:0x1700
	s_waitcnt lgkmcnt(2)
	v_mfma_f32_32x32x16_bf16 v[48:63], v[216:219], v[168:171], v[48:63]
	v_mfma_f32_32x32x16_bf16 v[16:31], v[212:215], v[168:171], v[16:31]
	s_waitcnt lgkmcnt(0)
	v_mfma_f32_32x32x16_bf16 v[48:63], v[224:227], v[172:175], v[48:63]
	v_mfma_f32_32x32x16_bf16 v[16:31], v[220:223], v[172:175], v[16:31]
	s_waitcnt lgkmcnt(0)
	v_mfma_f32_32x32x16_bf16 v[212:227], v[144:147], v[176:179], 0
	v_mfma_f32_32x32x16_bf16 v[212:227], v[148:151], v[180:183], v[212:227]
	v_mfma_f32_32x32x16_bf16 v[212:227], v[156:159], v[184:187], v[212:227]
	v_mfma_f32_32x32x16_bf16 v[212:227], v[244:247], v[188:191], v[212:227]
	ds_read_b128 v[144:147], v241 offset:0x2080
	ds_read_b128 v[148:151], v240 offset:0x2080
	ds_read_b128 v[152:155], v239 offset:0x2080
	ds_read_b128 v[156:159], v0 offset:0x2080
	v_cmp_eq_f32_e32 vcc, 0, v238
	v_cmp_eq_f32_e64 s[6:7], 0, v237
	s_and_b64 s[0:1], vcc, s[6:7]
	s_cmp_eq_u64 s[0:1], exec
	s_waitcnt lgkmcnt(0)
	v_mfma_f32_32x32x16_bf16 v[160:175], v[144:147], v[192:195], 0
	v_mfma_f32_32x32x16_bf16 v[160:175], v[148:151], v[196:199], v[160:175]
	v_mfma_f32_32x32x16_bf16 v[160:175], v[152:155], v[200:203], v[160:175]
	v_mfma_f32_32x32x16_bf16 v[160:175], v[156:159], v[204:207], v[160:175]
	s_cbranch_scc0 .Lfz2o_c2
	v_exp_f32_e32 v144, v212
	v_exp_f32_e32 v145, v213
	v_exp_f32_e32 v146, v214
	v_exp_f32_e32 v147, v215
	v_exp_f32_e32 v148, v216
	v_exp_f32_e32 v149, v217
	v_exp_f32_e32 v150, v218
	v_exp_f32_e32 v151, v219
	v_exp_f32_e32 v152, v220
	v_exp_f32_e32 v153, v221
	v_exp_f32_e32 v154, v222
	v_exp_f32_e32 v155, v223
	v_exp_f32_e32 v156, v224
	v_exp_f32_e32 v157, v225
	v_exp_f32_e32 v158, v226
	v_exp_f32_e32 v159, v227
	v_add_f32_e32 v252, v144, v145
	v_add_f32_e32 v253, v146, v147
	v_add_f32_e32 v254, v148, v149
	v_add_f32_e32 v255, v150, v151
	v_add_f32_e32 v252, v252, v152
	v_add_f32_e32 v253, v253, v153
	v_add_f32_e32 v254, v254, v154
	v_add_f32_e32 v255, v255, v155
	v_add_f32_e32 v252, v252, v156
	v_add_f32_e32 v253, v253, v157
	v_add_f32_e32 v254, v254, v158
	v_add_f32_e32 v255, v255, v159
	v_cvt_pk_bf16_f32 v6, v144, v145
	v_cvt_pk_bf16_f32 v7, v146, v147
	v_add_f32_e32 v252, v252, v253
	v_add_f32_e32 v254, v254, v255
	v_cvt_pk_bf16_f32 v8, v148, v149
	v_cvt_pk_bf16_f32 v9, v150, v151
	v_cvt_pk_bf16_f32 v208, v152, v153
	v_add_f32_e32 v252, v252, v254
	v_cvt_pk_bf16_f32 v209, v154, v155
	v_cvt_pk_bf16_f32 v210, v156, v157
	v_cvt_pk_bf16_f32 v211, v158, v159
	v_cmp_lt_f32_e32 vcc, s48, v252
	v_cmp_gt_f32_e64 s[6:7], s49, v252
	s_and_b64 s[0:1], vcc, s[6:7]
	s_cmp_lg_u64 s[0:1], exec
	s_cbranch_scc1 .LBB0_2152
	v_add_f32_e32 v15, v15, v252
	v_exp_f32_e32 v144, v160
	v_exp_f32_e32 v145, v161
	v_exp_f32_e32 v146, v162
	v_exp_f32_e32 v147, v163
	v_exp_f32_e32 v148, v164
	v_exp_f32_e32 v149, v165
	v_exp_f32_e32 v150, v166
	v_exp_f32_e32 v151, v167
	v_exp_f32_e32 v152, v168
	v_exp_f32_e32 v153, v169
	v_exp_f32_e32 v154, v170
	v_exp_f32_e32 v155, v171
	v_exp_f32_e32 v156, v172
	v_exp_f32_e32 v157, v173
	v_exp_f32_e32 v158, v174
	v_exp_f32_e32 v159, v175
	v_add_f32_e32 v252, v144, v145
	v_add_f32_e32 v253, v146, v147
	v_add_f32_e32 v254, v148, v149
	v_add_f32_e32 v255, v150, v151
	v_add_f32_e32 v252, v252, v152
	v_add_f32_e32 v253, v253, v153
	v_add_f32_e32 v254, v254, v154
	v_add_f32_e32 v255, v255, v155
	v_add_f32_e32 v252, v252, v156
	v_add_f32_e32 v253, v253, v157
	v_add_f32_e32 v254, v254, v158
	v_add_f32_e32 v255, v255, v159
	v_cvt_pk_bf16_f32 v2, v144, v145
	v_cvt_pk_bf16_f32 v3, v146, v147
	v_add_f32_e32 v252, v252, v253
	v_add_f32_e32 v254, v254, v255
	v_cvt_pk_bf16_f32 v4, v148, v149
	v_cvt_pk_bf16_f32 v5, v150, v151
	v_cvt_pk_bf16_f32 v10, v152, v153
	v_add_f32_e32 v252, v252, v254
	v_cvt_pk_bf16_f32 v11, v154, v155
	v_cvt_pk_bf16_f32 v12, v156, v157
	v_cvt_pk_bf16_f32 v13, v158, v159
	v_cmp_lt_f32_e32 vcc, s48, v252
	v_cmp_gt_f32_e64 s[6:7], s49, v252
	s_and_b64 s[0:1], vcc, s[6:7]
	s_cmp_lg_u64 s[0:1], exec
	s_cbranch_scc1 .Lfzsb2_c2
	v_add_f32_e32 v14, v14, v252
	s_branch .LBB0_2137
